# static s_setprio 1 for waves 4-7 at kernel entry (docs 6.3 priority raise for the younger half)
# speedup vs baseline: 1.0118x; 1.0004x over previous
; DEV int vhalf() { return __builtin_amdgcn_readfirstlane((int)(threadIdx.x >> 8)); }
; #define LAS __attribute__((address_space(3)))
; __global__ void __launch_bounds__(512) mk(Params p) {
;   cg::grid_group grid = cg::this_grid();
;   __shared__ __attribute__((aligned(16))) char smem[SMEM_BYTES];
;   __shared__ uint4 xb_words;
;   if (threadIdx.x == 0) xb_words = make_uint4(0u, 0u, 0u, 0u);
;   __syncthreads();
;   const XcdBarrier xb = xcd_barrier_post((unsigned*)(p.ws + OFF_XBAR), (volatile LAS unsigned*)&xb_words);
;   char* hsm = smem + vhalf() * HALF_BYTES;
_Z2mk6Params:
	s_load_dwordx4 s[88:91], s[0:1], 0xe0
	s_load_dwordx8 s[72:79], s[0:1], 0xc0
	s_add_u32 s10, s0, 0xe8
	v_and_b32_e32 v202, 0x3ff, v0
	s_mov_b32 s80, s2
	s_addc_u32 s11, s1, 0
	v_readfirstlane_b32 s100, v202
	s_nop 3
	s_lshr_b32 s100, s100, 6
	s_cmp_ge_u32 s100, 4
	s_cbranch_scc0 .Lprio_done
	s_setprio 1
.Lprio_done:
	v_cmp_ne_u32_e64 s[6:7], 0, v202
	v_cmp_eq_u32_e64 s[82:83], 0, v202
	s_and_saveexec_b64 s[2:3], s[82:83]
	s_cbranch_execz .LBB0_2
	v_mov_b32_e32 v2, 0
	v_mov_b32_e32 v3, v2
	v_mov_b32_e32 v4, v2
	v_mov_b32_e32 v5, v2
	v_mov_b32_e32 v1, 0x25800
	ds_write_b128 v1, v[2:5]
